# prologue weight conversion: batched row+gain loads per 64x64 tile (one wait instead of 8 serial round trips); K-loop head: LDS reads before pointer math, precomputed read bases
# speedup vs baseline: 1.0216x; 1.0101x over previous
; #define PG8_STAGE(bufoff, gbase, voff) do { _Pragma("unroll") for (int _i = 0; _i < 2; ++_i) \
;         __builtin_amdgcn_global_load_lds((const unsigned*)((const char*)(gbase) + (voff)[_i]), (PG8_LAS unsigned*)(lds + (bufoff) + ldsw + _i * 8192), 16, 0, 0); } while (0)
; #define PG8_LDA(dst, b, h) do { _Pragma("unroll") for (int m = 0; m < 4; ++m) _Pragma("unroll") for (int k = 0; k < 2; ++k) dst[m][k] = *(const PG8_LAS bf16x8*)(lds + PG8_SA(b, h) + aoff + m * 2048 + k * 1024); } while (0)
; #define PG8_LDB(dst, b, h) do { _Pragma("unroll") for (int n = 0; n < 2; ++n) _Pragma("unroll") for (int k = 0; k < 2; ++k) dst[n][k] = *(const PG8_LAS bf16x8*)(lds + PG8_SB(b, h) + boff + n * 2048 + k * 1024); } while (0)
; #define PG8_MMA(ai, bj, At, Bt) do { __builtin_amdgcn_s_setprio(1); _Pragma("unroll") for (int m = 0; m < 4; ++m) _Pragma("unroll") for (int n = 0; n < 2; ++n) _Pragma("unroll") for (int k = 0; k < 2; ++k) \
;         acc[ai][bj][m][n] = __builtin_amdgcn_mfma_f32_16x16x32_bf16(Bt[n][k], At[m][k], acc[ai][bj][m][n], 0, 0, 0); __builtin_amdgcn_s_setprio(0); } while (0)
; #define PG8_WAIT_V(n) asm volatile("s_waitcnt vmcnt(" #n ")" ::: "memory")
; #define PG8_WAIT_L(n) asm volatile("s_waitcnt lgkmcnt(" #n ")" ::: "memory")
; #define PG8_BAR __builtin_amdgcn_s_barrier()
; #define PG8_SCHED __builtin_amdgcn_sched_barrier(0)
; template <class Epi, class Sched, bool ALIGN_EPI = false, bool SP2 = false>
; __device__ __forceinline__ void gemm_phase(PG8_LAS unsigned char* lds, const Gemm g, const Sched& S, const Epi& E) {
;     ...
; #pragma unroll
;     for (int a = 0; a < 2; ++a)
; #pragma unroll
;         for (int b = 0; b < 2; ++b)
; #pragma unroll
;             for (int m = 0; m < 4; ++m)
; #pragma unroll
;                 for (int n = 0; n < 2; ++n) acc[a][b][m][n] = (f32x4){0.f, 0.f, 0.f, 0.f};
;     ...
;             PG8_LDB(B0, 0, 0); PG8_LDB(B1, 0, 1); PG8_SCHED; PG8_LDA(At, 0, 0); PG8_STAGE(PG8_SA(1, 1), a1 + hstepA, voffA);
;             PG8_WAIT_V(8); PG8_WAIT_L(0); PG8_BAR; PG8_MMA(0, 0, At, B0); PG8_MMA(0, 1, At, B1); PG8_BAR; PG8_SCHED;
.LBB0_205:
	v_readlane_b32 s28, v255, 0
	v_readlane_b32 s29, v255, 1
	s_andn2_b64 vcc, exec, s[28:29]
	s_cbranch_vccnz .LBB0_208
	s_add_u32 s28, s6, 0x100
	s_addc_u32 s29, s7, 0
	s_add_u32 s6, s16, 0x80
	v_mov_b32_e32 v0, 0
	s_addc_u32 s7, s17, 0
	s_mov_b32 s16, 0
	v_mov_b32_e32 v1, v0
	v_mov_b32_e32 v2, v0
	v_mov_b32_e32 v3, v0
	v_mov_b32_e32 v4, v0
	v_mov_b32_e32 v5, v0
	v_mov_b32_e32 v6, v0
	v_mov_b32_e32 v7, v0
	v_mov_b32_e32 v16, v0
	v_mov_b32_e32 v17, v0
	v_mov_b32_e32 v18, v0
	v_mov_b32_e32 v19, v0
	v_mov_b32_e32 v20, v0
	v_mov_b32_e32 v21, v0
	v_mov_b32_e32 v22, v0
	v_mov_b32_e32 v23, v0
	v_mov_b32_e32 v32, v0
	v_mov_b32_e32 v33, v0
	v_mov_b32_e32 v34, v0
	v_mov_b32_e32 v35, v0
	v_mov_b32_e32 v36, v0
	v_mov_b32_e32 v37, v0
	v_mov_b32_e32 v38, v0
	v_mov_b32_e32 v39, v0
	v_mov_b32_e32 v48, v0
	v_mov_b32_e32 v49, v0
	v_mov_b32_e32 v50, v0
	v_mov_b32_e32 v51, v0
	v_mov_b32_e32 v52, v0
	v_mov_b32_e32 v53, v0
	v_mov_b32_e32 v54, v0
	v_mov_b32_e32 v55, v0
	v_mov_b32_e32 v8, v0
	v_mov_b32_e32 v9, v0
	v_mov_b32_e32 v10, v0
	v_mov_b32_e32 v11, v0
	v_mov_b32_e32 v12, v0
	v_mov_b32_e32 v13, v0
	v_mov_b32_e32 v14, v0
	v_mov_b32_e32 v15, v0
	v_mov_b32_e32 v24, v0
	v_mov_b32_e32 v25, v0
	v_mov_b32_e32 v26, v0
	v_mov_b32_e32 v27, v0
	v_mov_b32_e32 v28, v0
	v_mov_b32_e32 v29, v0
	v_mov_b32_e32 v30, v0
	v_mov_b32_e32 v31, v0
	v_mov_b32_e32 v40, v0
	v_mov_b32_e32 v41, v0
	v_mov_b32_e32 v42, v0
	v_mov_b32_e32 v43, v0
	v_mov_b32_e32 v44, v0
	v_mov_b32_e32 v45, v0
	v_mov_b32_e32 v46, v0
	v_mov_b32_e32 v47, v0
	v_mov_b32_e32 v56, v0
	v_mov_b32_e32 v57, v0
	v_mov_b32_e32 v58, v0
	v_mov_b32_e32 v59, v0
	v_mov_b32_e32 v60, v0
	v_mov_b32_e32 v61, v0
	v_mov_b32_e32 v62, v0
	v_mov_b32_e32 v63, v0
	v_mov_b32_e32 v68, v0
	v_mov_b32_e32 v69, v0
	v_mov_b32_e32 v70, v0
	v_mov_b32_e32 v71, v0
	v_mov_b32_e32 v72, v0
	v_mov_b32_e32 v73, v0
	v_mov_b32_e32 v74, v0
	v_mov_b32_e32 v75, v0
	v_mov_b32_e32 v84, v0
	v_mov_b32_e32 v85, v0
	v_mov_b32_e32 v86, v0
	v_mov_b32_e32 v87, v0
	v_mov_b32_e32 v88, v0
	v_mov_b32_e32 v89, v0
	s_waitcnt vmcnt(0)
	v_mov_b32_e32 v90, v0
	v_mov_b32_e32 v91, v0
	v_mov_b32_e32 v100, v0
	v_mov_b32_e32 v101, v0
	v_mov_b32_e32 v102, v0
	v_mov_b32_e32 v103, v0
	v_mov_b32_e32 v104, v0
	v_mov_b32_e32 v105, v0
	v_mov_b32_e32 v106, v0
	v_mov_b32_e32 v107, v0
	v_mov_b32_e32 v116, v0
	v_mov_b32_e32 v117, v0
	v_mov_b32_e32 v118, v0
	v_mov_b32_e32 v119, v0
	v_mov_b32_e32 v120, v0
	v_mov_b32_e32 v121, v0
	v_mov_b32_e32 v122, v0
	v_mov_b32_e32 v123, v0
	v_mov_b32_e32 v76, v0
	v_mov_b32_e32 v77, v0
	v_mov_b32_e32 v78, v0
	v_mov_b32_e32 v79, v0
	v_mov_b32_e32 v80, v0
	v_mov_b32_e32 v81, v0
	v_mov_b32_e32 v82, v0
	v_mov_b32_e32 v83, v0
	v_mov_b32_e32 v92, v0
	v_mov_b32_e32 v93, v0
	v_mov_b32_e32 v94, v0
	v_mov_b32_e32 v95, v0
	v_mov_b32_e32 v96, v0
	v_mov_b32_e32 v97, v0
	v_mov_b32_e32 v98, v0
	v_mov_b32_e32 v99, v0
	v_mov_b32_e32 v108, v0
	v_mov_b32_e32 v109, v0
	v_mov_b32_e32 v110, v0
	v_mov_b32_e32 v111, v0
	v_mov_b32_e32 v112, v0
	v_mov_b32_e32 v113, v0
	v_mov_b32_e32 v114, v0
	v_mov_b32_e32 v115, v0
	v_mov_b32_e32 v124, v0
	v_mov_b32_e32 v125, v0
	v_mov_b32_e32 v126, v0
	v_mov_b32_e32 v127, v0
	v_mov_b32_e32 v128, v0
	v_mov_b32_e32 v129, v0
	v_mov_b32_e32 v130, v0
	v_mov_b32_e32 v131, v0
	v_add_u32_e32 v236, 0x10000, v209
	v_add_u32_e32 v237, 0x14000, v209
	v_add_u32_e32 v238, 0x18000, v209
	v_add_u32_e32 v239, 0x1c000, v209
.LBB0_207:
	s_waitcnt lgkmcnt(0)
	ds_read_b128 v[132:135], v236
	ds_read_b128 v[136:139], v236 offset:1024
	ds_read_b128 v[140:143], v236 offset:2048
	ds_read_b128 v[144:147], v236 offset:3072
	ds_read_b128 v[148:151], v237
	ds_read_b128 v[152:155], v237 offset:1024
	ds_read_b128 v[182:185], v237 offset:2048
	ds_read_b128 v[186:189], v237 offset:3072
	s_add_i32 s30, s16, 2
	s_add_u32 s31, s6, 0x80
	s_addc_u32 s17, s7, 0
	s_add_i32 s36, 0, 0x10000
	s_cmp_eq_u32 s88, s16
	s_cselect_b32 s17, s79, s17
	s_cselect_b32 s16, s78, s31
	s_cselect_b32 s35, s81, s29
	s_cselect_b32 s34, s80, s28
	s_add_i32 s31, 0, 0x14000
	s_add_i32 m0, s9, 0xc000
	ds_read_b128 v[190:193], v216
	ds_read_b128 v[194:197], v216 offset:1024
	ds_read_b128 v[198:201], v216 offset:2048
	ds_read_b128 v[202:205], v216 offset:3072
	ds_read_b128 v[220:223], v216 offset:4096
	ds_read_b128 v[224:227], v216 offset:5120
	ds_read_b128 v[228:231], v216 offset:6144
	ds_read_b128 v[232:235], v216 offset:7168
	global_load_lds_dwordx4 v180, s[6:7]
	s_add_i32 m0, s9, 0xe000
	s_nop 0
	global_load_lds_dwordx4 v178, s[6:7]
	s_waitcnt vmcnt(8)
	s_waitcnt lgkmcnt(0)
	s_barrier
; #define PG8_STAGE(bufoff, gbase, voff) do { _Pragma("unroll") for (int _i = 0; _i < 2; ++_i) \
;         __builtin_amdgcn_global_load_lds((const unsigned*)((const char*)(gbase) + (voff)[_i]), (PG8_LAS unsigned*)(lds + (bufoff) + ldsw + _i * 8192), 16, 0, 0); } while (0)
; #define PG8_LDA(dst, b, h) do { _Pragma("unroll") for (int m = 0; m < 4; ++m) _Pragma("unroll") for (int k = 0; k < 2; ++k) dst[m][k] = *(const PG8_LAS bf16x8*)(lds + PG8_SA(b, h) + aoff + m * 2048 + k * 1024); } while (0)
; #define PG8_MMA(ai, bj, At, Bt) do { __builtin_amdgcn_s_setprio(1); _Pragma("unroll") for (int m = 0; m < 4; ++m) _Pragma("unroll") for (int n = 0; n < 2; ++n) _Pragma("unroll") for (int k = 0; k < 2; ++k) \
;         acc[ai][bj][m][n] = __builtin_amdgcn_mfma_f32_16x16x32_bf16(Bt[n][k], At[m][k], acc[ai][bj][m][n], 0, 0, 0); __builtin_amdgcn_s_setprio(0); } while (0)
; #define PG8_WAIT_V(n) asm volatile("s_waitcnt vmcnt(" #n ")" ::: "memory")
; #define PG8_WAIT_L(n) asm volatile("s_waitcnt lgkmcnt(" #n ")" ::: "memory")
; #define PG8_BAR __builtin_amdgcn_s_barrier()
; #define PG8_SCHED __builtin_amdgcn_sched_barrier(0)
; template <class Epi, class Sched, bool ALIGN_EPI = false, bool SP2 = false>
; __device__ __forceinline__ void gemm_phase(PG8_LAS unsigned char* lds, const Gemm g, const Sched& S, const Epi& E) {
;     ...
;             PG8_WAIT_V(8); PG8_WAIT_L(0); PG8_BAR; PG8_MMA(0, 0, At, B0); PG8_MMA(0, 1, At, B1); PG8_BAR; PG8_SCHED;
;             PG8_LDA(At, 0, 1); PG8_STAGE(PG8_SB(0, 0), b2, voffB); PG8_STAGE(PG8_SB(0, 1), b2 + hstepB, voffB); PG8_STAGE(PG8_SA(0, 0), a2, voffA);
;             PG8_WAIT_V(8); PG8_WAIT_L(0); PG8_BAR; PG8_MMA(1, 0, At, B0); PG8_MMA(1, 1, At, B1); PG8_BAR; PG8_SCHED;
	s_setprio 1
	s_waitcnt lgkmcnt(0)
	v_mfma_f32_16x16x32_bf16 v[128:131], v[132:135], v[190:193], v[128:131]
	v_mfma_f32_16x16x32_bf16 v[124:127], v[140:143], v[190:193], v[124:127]
	v_mfma_f32_16x16x32_bf16 v[112:115], v[132:135], v[198:201], v[112:115]
	v_mfma_f32_16x16x32_bf16 v[108:111], v[140:143], v[198:201], v[108:111]
	v_mfma_f32_16x16x32_bf16 v[96:99], v[132:135], v[220:223], v[96:99]
	v_mfma_f32_16x16x32_bf16 v[92:95], v[140:143], v[220:223], v[92:95]
	v_mfma_f32_16x16x32_bf16 v[80:83], v[132:135], v[228:231], v[80:83]
	v_mfma_f32_16x16x32_bf16 v[76:79], v[140:143], v[228:231], v[76:79]
	v_mfma_f32_16x16x32_bf16 v[128:131], v[136:139], v[194:197], v[128:131]
	v_mfma_f32_16x16x32_bf16 v[124:127], v[144:147], v[194:197], v[124:127]
	v_mfma_f32_16x16x32_bf16 v[112:115], v[136:139], v[202:205], v[112:115]
	v_mfma_f32_16x16x32_bf16 v[108:111], v[144:147], v[202:205], v[108:111]
	v_mfma_f32_16x16x32_bf16 v[96:99], v[136:139], v[224:227], v[96:99]
	v_mfma_f32_16x16x32_bf16 v[92:95], v[144:147], v[224:227], v[92:95]
	v_mfma_f32_16x16x32_bf16 v[80:83], v[136:139], v[232:235], v[80:83]
	v_mfma_f32_16x16x32_bf16 v[76:79], v[144:147], v[232:235], v[76:79]
	s_setprio 0
	s_setprio 1
	v_mfma_f32_16x16x32_bf16 v[120:123], v[148:151], v[190:193], v[120:123]
	v_mfma_f32_16x16x32_bf16 v[116:119], v[182:185], v[190:193], v[116:119]
	v_mfma_f32_16x16x32_bf16 v[104:107], v[148:151], v[198:201], v[104:107]
	v_mfma_f32_16x16x32_bf16 v[100:103], v[182:185], v[198:201], v[100:103]
	v_mfma_f32_16x16x32_bf16 v[88:91], v[148:151], v[220:223], v[88:91]
	v_mfma_f32_16x16x32_bf16 v[84:87], v[182:185], v[220:223], v[84:87]
	v_mfma_f32_16x16x32_bf16 v[72:75], v[148:151], v[228:231], v[72:75]
	v_mfma_f32_16x16x32_bf16 v[66:69], v[182:185], v[228:231], v[68:71]
	v_mfma_f32_16x16x32_bf16 v[120:123], v[152:155], v[194:197], v[120:123]
	v_mfma_f32_16x16x32_bf16 v[116:119], v[186:189], v[194:197], v[116:119]
	v_mfma_f32_16x16x32_bf16 v[104:107], v[152:155], v[202:205], v[104:107]
	v_mfma_f32_16x16x32_bf16 v[100:103], v[186:189], v[202:205], v[100:103]
	v_mfma_f32_16x16x32_bf16 v[88:91], v[152:155], v[224:227], v[88:91]
	v_mfma_f32_16x16x32_bf16 v[84:87], v[186:189], v[224:227], v[84:87]
	v_mfma_f32_16x16x32_bf16 v[72:75], v[152:155], v[232:235], v[72:75]
	v_mfma_f32_16x16x32_bf16 v[66:69], v[186:189], v[232:235], v[66:69]
	s_setprio 0
	s_barrier
	s_add_i32 s36, s36, s8
	s_mov_b32 m0, s36
	ds_read_b128 v[190:193], v216 offset:16384
	ds_read_b128 v[194:197], v216 offset:17408
	ds_read_b128 v[198:201], v216 offset:18432
	ds_read_b128 v[202:205], v216 offset:19456
	ds_read_b128 v[220:223], v216 offset:20480
	ds_read_b128 v[224:227], v216 offset:21504
	ds_read_b128 v[228:231], v216 offset:22528
	ds_read_b128 v[232:235], v216 offset:23552
	global_load_lds_dwordx4 v160, s[34:35]
	s_add_i32 m0, s36, 0x2000
	s_add_u32 s100, s34, s60
	s_addc_u32 s101, s35, s61
	s_add_i32 s31, s31, s8
	global_load_lds_dwordx4 v164, s[34:35]
	s_add_u32 s34, s34, s94
	s_addc_u32 s35, s35, 0
	s_mov_b32 m0, s31
	s_add_u32 vcc_lo, s16, s60
	s_addc_u32 vcc_hi, s17, s61
	global_load_lds_dwordx4 v160, s[34:35]
	s_add_i32 m0, s31, 0x2000
	s_nop 0
	global_load_lds_dwordx4 v164, s[34:35]
	s_mov_b32 m0, s9
	s_nop 0
	global_load_lds_dwordx4 v158, s[16:17]
	s_mov_b32 m0, s71
	s_nop 0
	global_load_lds_dwordx4 v162, s[16:17]
	s_waitcnt vmcnt(8)
	s_waitcnt lgkmcnt(0)
	s_barrier
	s_setprio 1
	s_waitcnt lgkmcnt(0)
	v_mfma_f32_16x16x32_bf16 v[60:63], v[132:135], v[190:193], v[60:63]
	v_mfma_f32_16x16x32_bf16 v[56:59], v[140:143], v[190:193], v[56:59]
	v_mfma_f32_16x16x32_bf16 v[44:47], v[132:135], v[198:201], v[44:47]
	v_mfma_f32_16x16x32_bf16 v[40:43], v[140:143], v[198:201], v[40:43]
	v_mfma_f32_16x16x32_bf16 v[28:31], v[132:135], v[220:223], v[28:31]
	v_mfma_f32_16x16x32_bf16 v[24:27], v[140:143], v[220:223], v[24:27]
	v_mfma_f32_16x16x32_bf16 v[12:15], v[132:135], v[228:231], v[12:15]
	v_mfma_f32_16x16x32_bf16 v[8:11], v[140:143], v[228:231], v[8:11]
	v_mfma_f32_16x16x32_bf16 v[60:63], v[136:139], v[194:197], v[60:63]
	v_mfma_f32_16x16x32_bf16 v[56:59], v[144:147], v[194:197], v[56:59]
	v_mfma_f32_16x16x32_bf16 v[44:47], v[136:139], v[202:205], v[44:47]
	v_mfma_f32_16x16x32_bf16 v[40:43], v[144:147], v[202:205], v[40:43]
	v_mfma_f32_16x16x32_bf16 v[28:31], v[136:139], v[224:227], v[28:31]
	v_mfma_f32_16x16x32_bf16 v[24:27], v[144:147], v[224:227], v[24:27]
	v_mfma_f32_16x16x32_bf16 v[12:15], v[136:139], v[232:235], v[12:15]
	v_mfma_f32_16x16x32_bf16 v[8:11], v[144:147], v[232:235], v[8:11]
	s_setprio 0
	s_setprio 1
	v_mfma_f32_16x16x32_bf16 v[52:55], v[148:151], v[190:193], v[52:55]
	v_mfma_f32_16x16x32_bf16 v[48:51], v[182:185], v[190:193], v[48:51]
	v_mfma_f32_16x16x32_bf16 v[36:39], v[148:151], v[198:201], v[36:39]
	v_mfma_f32_16x16x32_bf16 v[32:35], v[182:185], v[198:201], v[32:35]
	v_mfma_f32_16x16x32_bf16 v[20:23], v[148:151], v[220:223], v[20:23]
	v_mfma_f32_16x16x32_bf16 v[16:19], v[182:185], v[220:223], v[16:19]
	v_mfma_f32_16x16x32_bf16 v[4:7], v[148:151], v[228:231], v[4:7]
	v_mfma_f32_16x16x32_bf16 v[0:3], v[182:185], v[228:231], v[0:3]
	v_mfma_f32_16x16x32_bf16 v[52:55], v[152:155], v[194:197], v[52:55]
	v_mfma_f32_16x16x32_bf16 v[48:51], v[186:189], v[194:197], v[48:51]
	v_mfma_f32_16x16x32_bf16 v[36:39], v[152:155], v[202:205], v[36:39]
	v_mfma_f32_16x16x32_bf16 v[32:35], v[186:189], v[202:205], v[32:35]
	v_mfma_f32_16x16x32_bf16 v[20:23], v[152:155], v[224:227], v[20:23]
	v_mfma_f32_16x16x32_bf16 v[16:19], v[186:189], v[224:227], v[16:19]
	v_mfma_f32_16x16x32_bf16 v[4:7], v[152:155], v[232:235], v[4:7]
	v_mfma_f32_16x16x32_bf16 v[0:3], v[186:189], v[232:235], v[0:3]
	s_setprio 0
	s_barrier
; #define PG8_STAGE(bufoff, gbase, voff) do { _Pragma("unroll") for (int _i = 0; _i < 2; ++_i) \
;         __builtin_amdgcn_global_load_lds((const unsigned*)((const char*)(gbase) + (voff)[_i]), (PG8_LAS unsigned*)(lds + (bufoff) + ldsw + _i * 8192), 16, 0, 0); } while (0)
; #define PG8_LDA(dst, b, h) do { _Pragma("unroll") for (int m = 0; m < 4; ++m) _Pragma("unroll") for (int k = 0; k < 2; ++k) dst[m][k] = *(const PG8_LAS bf16x8*)(lds + PG8_SA(b, h) + aoff + m * 2048 + k * 1024); } while (0)
; #define PG8_LDB(dst, b, h) do { _Pragma("unroll") for (int n = 0; n < 2; ++n) _Pragma("unroll") for (int k = 0; k < 2; ++k) dst[n][k] = *(const PG8_LAS bf16x8*)(lds + PG8_SB(b, h) + boff + n * 2048 + k * 1024); } while (0)
; #define PG8_MMA(ai, bj, At, Bt) do { __builtin_amdgcn_s_setprio(1); _Pragma("unroll") for (int m = 0; m < 4; ++m) _Pragma("unroll") for (int n = 0; n < 2; ++n) _Pragma("unroll") for (int k = 0; k < 2; ++k) \
;         acc[ai][bj][m][n] = __builtin_amdgcn_mfma_f32_16x16x32_bf16(Bt[n][k], At[m][k], acc[ai][bj][m][n], 0, 0, 0); __builtin_amdgcn_s_setprio(0); } while (0)
; #define PG8_WAIT_V(n) asm volatile("s_waitcnt vmcnt(" #n ")" ::: "memory")
; #define PG8_WAIT_L(n) asm volatile("s_waitcnt lgkmcnt(" #n ")" ::: "memory")
; #define PG8_BAR __builtin_amdgcn_s_barrier()
; #define PG8_SCHED __builtin_amdgcn_sched_barrier(0)
; template <class Epi, class Sched, bool ALIGN_EPI = false, bool SP2 = false>
; __device__ __forceinline__ void gemm_phase(PG8_LAS unsigned char* lds, const Gemm g, const Sched& S, const Epi& E) {
;     ...
;         for (int t = 0; t < nt; t += 2) {
;     ...
;             PG8_LDB(B0, 1, 0); PG8_LDB(B1, 1, 1); PG8_SCHED; PG8_LDA(At, 1, 0); PG8_STAGE(PG8_SA(0, 1), a2 + hstepA, voffA);
;             PG8_WAIT_V(8); PG8_WAIT_L(0); PG8_BAR; PG8_MMA(0, 0, At, B0); PG8_MMA(0, 1, At, B1); PG8_BAR; PG8_SCHED;
;             PG8_LDA(At, 1, 1); PG8_STAGE(PG8_SB(1, 0), b3, voffB); PG8_STAGE(PG8_SB(1, 1), b3 + hstepB, voffB); PG8_STAGE(PG8_SA(1, 0), a3, voffA);
;             PG8_WAIT_V(8); PG8_WAIT_L(0); PG8_BAR; PG8_MMA(1, 0, At, B0); PG8_MMA(1, 1, At, B1); PG8_BAR; PG8_SCHED;
	ds_read_b128 v[132:135], v238
	ds_read_b128 v[136:139], v238 offset:1024
	ds_read_b128 v[140:143], v238 offset:2048
	ds_read_b128 v[144:147], v238 offset:3072
	ds_read_b128 v[148:151], v239
	ds_read_b128 v[152:155], v239 offset:1024
	ds_read_b128 v[182:185], v239 offset:2048
	ds_read_b128 v[186:189], v239 offset:3072
	s_add_i32 s34, 0, 0x1c000
	s_add_i32 s31, 0, 0x18000
	s_add_u32 s16, s16, s94
	s_addc_u32 s17, s17, 0
	s_mov_b32 m0, s12
	ds_read_b128 v[190:193], v216 offset:32768
	ds_read_b128 v[194:197], v216 offset:33792
	ds_read_b128 v[198:201], v216 offset:34816
	ds_read_b128 v[202:205], v216 offset:35840
	ds_read_b128 v[220:223], v216 offset:36864
	ds_read_b128 v[224:227], v216 offset:37888
	ds_read_b128 v[228:231], v216 offset:38912
	ds_read_b128 v[232:235], v216 offset:39936
	global_load_lds_dwordx4 v158, s[16:17]
	s_mov_b32 m0, s13
	s_nop 0
	global_load_lds_dwordx4 v162, s[16:17]
	s_waitcnt vmcnt(8)
	s_waitcnt lgkmcnt(0)
	s_barrier
	s_setprio 1
	s_waitcnt lgkmcnt(0)
	v_mfma_f32_16x16x32_bf16 v[128:131], v[132:135], v[190:193], v[128:131]
	v_mfma_f32_16x16x32_bf16 v[124:127], v[140:143], v[190:193], v[124:127]
	v_mfma_f32_16x16x32_bf16 v[112:115], v[132:135], v[198:201], v[112:115]
	v_mfma_f32_16x16x32_bf16 v[108:111], v[140:143], v[198:201], v[108:111]
	v_mfma_f32_16x16x32_bf16 v[96:99], v[132:135], v[220:223], v[96:99]
	v_mfma_f32_16x16x32_bf16 v[92:95], v[140:143], v[220:223], v[92:95]
	v_mfma_f32_16x16x32_bf16 v[80:83], v[132:135], v[228:231], v[80:83]
	v_mfma_f32_16x16x32_bf16 v[76:79], v[140:143], v[228:231], v[76:79]
	v_mfma_f32_16x16x32_bf16 v[128:131], v[136:139], v[194:197], v[128:131]
	v_mfma_f32_16x16x32_bf16 v[124:127], v[144:147], v[194:197], v[124:127]
	v_mfma_f32_16x16x32_bf16 v[112:115], v[136:139], v[202:205], v[112:115]
	v_mfma_f32_16x16x32_bf16 v[108:111], v[144:147], v[202:205], v[108:111]
	v_mfma_f32_16x16x32_bf16 v[96:99], v[136:139], v[224:227], v[96:99]
	v_mfma_f32_16x16x32_bf16 v[92:95], v[144:147], v[224:227], v[92:95]
	v_mfma_f32_16x16x32_bf16 v[80:83], v[136:139], v[232:235], v[80:83]
	v_mfma_f32_16x16x32_bf16 v[76:79], v[144:147], v[232:235], v[76:79]
	s_setprio 0
	s_setprio 1
	v_mfma_f32_16x16x32_bf16 v[120:123], v[148:151], v[190:193], v[120:123]
	v_mfma_f32_16x16x32_bf16 v[116:119], v[182:185], v[190:193], v[116:119]
	v_mfma_f32_16x16x32_bf16 v[104:107], v[148:151], v[198:201], v[104:107]
	v_mfma_f32_16x16x32_bf16 v[100:103], v[182:185], v[198:201], v[100:103]
	v_mfma_f32_16x16x32_bf16 v[88:91], v[148:151], v[220:223], v[88:91]
	v_mfma_f32_16x16x32_bf16 v[84:87], v[182:185], v[220:223], v[84:87]
	v_mfma_f32_16x16x32_bf16 v[70:73], v[148:151], v[228:231], v[72:75]
	v_mfma_f32_16x16x32_bf16 v[66:69], v[182:185], v[228:231], v[66:69]
	v_mfma_f32_16x16x32_bf16 v[120:123], v[152:155], v[194:197], v[120:123]
	v_mfma_f32_16x16x32_bf16 v[116:119], v[186:189], v[194:197], v[116:119]
	v_mfma_f32_16x16x32_bf16 v[104:107], v[152:155], v[202:205], v[104:107]
	v_mfma_f32_16x16x32_bf16 v[100:103], v[186:189], v[202:205], v[100:103]
	v_mfma_f32_16x16x32_bf16 v[88:91], v[152:155], v[224:227], v[88:91]
	v_mfma_f32_16x16x32_bf16 v[84:87], v[186:189], v[224:227], v[84:87]
	v_mfma_f32_16x16x32_bf16 v[72:75], v[152:155], v[232:235], v[70:73]
	v_mfma_f32_16x16x32_bf16 v[68:71], v[186:189], v[232:235], v[66:69]
	s_setprio 0
	s_barrier
	s_add_i32 s16, s31, s8
	s_mov_b32 m0, s16
	ds_read_b128 v[190:193], v216 offset:49152
	ds_read_b128 v[194:197], v216 offset:50176
	ds_read_b128 v[198:201], v216 offset:51200
	ds_read_b128 v[202:205], v216 offset:52224
	ds_read_b128 v[220:223], v216 offset:53248
	ds_read_b128 v[224:227], v216 offset:54272
	ds_read_b128 v[228:231], v216 offset:55296
	ds_read_b128 v[232:235], v216 offset:56320
	global_load_lds_dwordx4 v160, s[100:101]
	s_add_i32 m0, s16, 0x2000
	s_add_i32 s16, s34, s8
	global_load_lds_dwordx4 v164, s[100:101]
	s_add_u32 s100, s100, s94
	s_addc_u32 s101, s101, 0
	s_mov_b32 m0, s16
	s_add_u32 s28, s28, 0x100
	s_addc_u32 s29, s29, 0
	global_load_lds_dwordx4 v160, s[100:101]
	s_add_i32 m0, s16, 0x2000
	s_add_u32 s6, s6, 0x100
	s_addc_u32 s7, s7, 0
	global_load_lds_dwordx4 v164, s[100:101]
	s_mov_b32 m0, s2
	s_nop 0
	global_load_lds_dwordx4 v158, vcc
	s_mov_b32 m0, s33
	s_nop 0
	global_load_lds_dwordx4 v162, vcc
	s_waitcnt vmcnt(8)
	s_waitcnt lgkmcnt(0)
	s_barrier
	s_setprio 1
	s_waitcnt lgkmcnt(0)
	v_mfma_f32_16x16x32_bf16 v[60:63], v[132:135], v[190:193], v[60:63]
	v_mfma_f32_16x16x32_bf16 v[56:59], v[140:143], v[190:193], v[56:59]
	v_mfma_f32_16x16x32_bf16 v[44:47], v[132:135], v[198:201], v[44:47]
	v_mfma_f32_16x16x32_bf16 v[40:43], v[140:143], v[198:201], v[40:43]
	v_mfma_f32_16x16x32_bf16 v[28:31], v[132:135], v[220:223], v[28:31]
	v_mfma_f32_16x16x32_bf16 v[24:27], v[140:143], v[220:223], v[24:27]
	v_mfma_f32_16x16x32_bf16 v[12:15], v[132:135], v[228:231], v[12:15]
	v_mfma_f32_16x16x32_bf16 v[8:11], v[140:143], v[228:231], v[8:11]
	v_mfma_f32_16x16x32_bf16 v[60:63], v[136:139], v[194:197], v[60:63]
	v_mfma_f32_16x16x32_bf16 v[56:59], v[144:147], v[194:197], v[56:59]
	v_mfma_f32_16x16x32_bf16 v[44:47], v[136:139], v[202:205], v[44:47]
	v_mfma_f32_16x16x32_bf16 v[40:43], v[144:147], v[202:205], v[40:43]
	v_mfma_f32_16x16x32_bf16 v[28:31], v[136:139], v[224:227], v[28:31]
	v_mfma_f32_16x16x32_bf16 v[24:27], v[144:147], v[224:227], v[24:27]
	v_mfma_f32_16x16x32_bf16 v[12:15], v[136:139], v[232:235], v[12:15]
	v_mfma_f32_16x16x32_bf16 v[8:11], v[144:147], v[232:235], v[8:11]
	s_setprio 0
	s_setprio 1
	v_mfma_f32_16x16x32_bf16 v[52:55], v[148:151], v[190:193], v[52:55]
	v_mfma_f32_16x16x32_bf16 v[48:51], v[182:185], v[190:193], v[48:51]
	v_mfma_f32_16x16x32_bf16 v[36:39], v[148:151], v[198:201], v[36:39]
	v_mfma_f32_16x16x32_bf16 v[32:35], v[182:185], v[198:201], v[32:35]
	v_mfma_f32_16x16x32_bf16 v[20:23], v[148:151], v[220:223], v[20:23]
	v_mfma_f32_16x16x32_bf16 v[16:19], v[182:185], v[220:223], v[16:19]
	v_mfma_f32_16x16x32_bf16 v[4:7], v[148:151], v[228:231], v[4:7]
	v_mfma_f32_16x16x32_bf16 v[0:3], v[182:185], v[228:231], v[0:3]
	v_mfma_f32_16x16x32_bf16 v[52:55], v[152:155], v[194:197], v[52:55]
	v_mfma_f32_16x16x32_bf16 v[48:51], v[186:189], v[194:197], v[48:51]
	v_mfma_f32_16x16x32_bf16 v[36:39], v[152:155], v[202:205], v[36:39]
	v_mfma_f32_16x16x32_bf16 v[32:35], v[186:189], v[202:205], v[32:35]
	v_mfma_f32_16x16x32_bf16 v[20:23], v[152:155], v[224:227], v[20:23]
	v_mfma_f32_16x16x32_bf16 v[16:19], v[186:189], v[224:227], v[16:19]
	v_mfma_f32_16x16x32_bf16 v[4:7], v[152:155], v[232:235], v[4:7]
	v_mfma_f32_16x16x32_bf16 v[0:3], v[186:189], v[232:235], v[0:3]
	s_setprio 0
	s_barrier
	s_cmp_ge_u32 s30, s24
	s_mov_b32 s16, s30
	s_cbranch_scc0 .LBB0_207
	s_branch .LBB0_209

; template <class F> DI void cvt_wT(const float* W, int K, int Ns, bf16_t* Wt, int Nd, F smap, float* sl, const float* gsc = nullptr) {
;     ...
;         const int j = tid & 63, i = tid >> 6;
;         __syncthreads();
; #pragma unroll
;         for (int r = 0; r < 8; ++r) { const int k = k0 + i * 8 + r; float v = 0.f; if (s0 >= 0 && s0 + j < Ns) v = W[(size_t)k * Ns + s0 + j]; if (gsc) v *= gsc[k]; sl[(i * 8 + r) * 65 + j] = v; }
;         __syncthreads();
.LBB0_533:
	s_mul_hi_i32 s6, s26, 0x66666667
	s_lshr_b32 s7, s6, 31
	s_ashr_i32 s6, s6, 4
	s_add_i32 s6, s6, s7
	s_mul_i32 s7, s6, 0xffffffd8
	s_mul_i32 s20, s6, 0xfffff600
	s_add_i32 s7, s26, s7
	s_add_i32 s98, s28, s20
	s_lshl_b32 s20, s6, 6
	s_cmp_gt_i32 s7, -1
	v_add_u32_e32 v3, s98, v6
	s_movk_i32 s21, 0xa00
	s_cselect_b64 s[6:7], -1, 0
	v_cmp_gt_i32_e32 vcc, s21, v3
	v_add_u32_e32 v2, s20, v8
	s_and_b64 s[22:23], s[6:7], vcc
	v_lshl_add_u64 v[4:5], s[98:99], 2, v[0:1]
	v_mov_b32_e32 v12, 0
	s_waitcnt vmcnt(0)
	s_barrier
	v_mov_b32_e32 v40, 0
	v_mov_b32_e32 v41, 0
	v_mov_b32_e32 v42, 0
	v_mov_b32_e32 v43, 0
	v_mov_b32_e32 v44, 0
	v_mov_b32_e32 v45, 0
	v_mov_b32_e32 v46, 0
	v_mov_b32_e32 v47, 0
	s_and_saveexec_b64 s[24:25], s[22:23]
	v_mad_i64_i32 v[56:57], vcc, v2, s3, v[4:5]
	global_load_dword v40, v[56:57], off
	v_or_b32_e32 v56, 1, v2
	v_mad_i64_i32 v[56:57], vcc, v56, s3, v[4:5]
	global_load_dword v41, v[56:57], off
	v_or_b32_e32 v56, 2, v2
	v_mad_i64_i32 v[56:57], vcc, v56, s3, v[4:5]
	global_load_dword v42, v[56:57], off
	v_or_b32_e32 v56, 3, v2
	v_mad_i64_i32 v[56:57], vcc, v56, s3, v[4:5]
	global_load_dword v43, v[56:57], off
	v_or_b32_e32 v56, 4, v2
	v_mad_i64_i32 v[56:57], vcc, v56, s3, v[4:5]
	global_load_dword v44, v[56:57], off
	v_or_b32_e32 v56, 5, v2
	v_mad_i64_i32 v[56:57], vcc, v56, s3, v[4:5]
	global_load_dword v45, v[56:57], off
	v_or_b32_e32 v56, 6, v2
	v_mad_i64_i32 v[56:57], vcc, v56, s3, v[4:5]
	global_load_dword v46, v[56:57], off
	v_or_b32_e32 v56, 7, v2
	v_mad_i64_i32 v[56:57], vcc, v56, s3, v[4:5]
	global_load_dword v47, v[56:57], off
	s_or_b64 exec, exec, s[24:25]
	s_andn2_b64 vcc, exec, s[0:1]
	s_cbranch_vccnz .Lcvt_nog_0
	v_ashrrev_i32_e32 v3, 31, v2
	v_lshl_add_u64 v[14:15], v[2:3], 2, s[14:15]
	global_load_dword v48, v[14:15], off
	global_load_dword v49, v[14:15], off offset:4
	global_load_dword v50, v[14:15], off offset:8
	global_load_dword v51, v[14:15], off offset:12
	global_load_dword v52, v[14:15], off offset:16
	global_load_dword v53, v[14:15], off offset:20
	global_load_dword v54, v[14:15], off offset:24
	global_load_dword v55, v[14:15], off offset:28
	s_waitcnt vmcnt(0)
	v_mul_f32_e32 v40, v40, v48
	v_mul_f32_e32 v41, v41, v49
	v_mul_f32_e32 v42, v42, v50
	v_mul_f32_e32 v43, v43, v51
	v_mul_f32_e32 v44, v44, v52
	v_mul_f32_e32 v45, v45, v53
	v_mul_f32_e32 v46, v46, v54
	v_mul_f32_e32 v47, v47, v55
.Lcvt_nog_0:
	s_waitcnt vmcnt(0)
	ds_write_b32 v11, v40
	ds_write_b32 v11, v41 offset:260
	ds_write_b32 v11, v42 offset:520
	ds_write_b32 v11, v43 offset:780
	ds_write_b32 v11, v44 offset:1040
	ds_write_b32 v11, v45 offset:1300
	ds_write_b32 v11, v46 offset:1560
	v_mov_b32_e32 v12, v47
	s_branch .LBB0_532

; template <class F> DI void cvt_wT(const float* W, int K, int Ns, bf16_t* Wt, int Nd, F smap, float* sl, const float* gsc = nullptr) {
;     ...
;         const int j = tid & 63, i = tid >> 6;
;         __syncthreads();
; #pragma unroll
;         for (int r = 0; r < 8; ++r) { const int k = k0 + i * 8 + r; float v = 0.f; if (s0 >= 0 && s0 + j < Ns) v = W[(size_t)k * Ns + s0 + j]; if (gsc) v *= gsc[k]; sl[(i * 8 + r) * 65 + j] = v; }
;         __syncthreads();
.LBB0_575:
	s_mul_hi_i32 s6, s42, 0x2aaaaaab
	s_lshr_b32 s7, s6, 31
	s_ashr_i32 s6, s6, 1
	s_add_i32 s6, s6, s7
	s_mul_i32 s7, s6, -12
	s_mul_i32 s24, s6, 0xfffffd00
	s_add_i32 s7, s42, s7
	s_add_i32 s98, s44, s24
	s_lshl_b32 s24, s6, 6
	s_cmp_gt_i32 s7, -1
	v_add_u32_e32 v3, s98, v6
	s_movk_i32 s25, 0x2a0
	s_cselect_b64 s[6:7], -1, 0
	v_cmp_gt_i32_e32 vcc, s25, v3
	v_add_u32_e32 v2, s24, v8
	s_and_b64 s[26:27], s[6:7], vcc
	v_lshl_add_u64 v[4:5], s[98:99], 2, v[0:1]
	v_mov_b32_e32 v12, 0
	s_barrier
	v_mov_b32_e32 v40, 0
	v_mov_b32_e32 v41, 0
	v_mov_b32_e32 v42, 0
	v_mov_b32_e32 v43, 0
	v_mov_b32_e32 v44, 0
	v_mov_b32_e32 v45, 0
	v_mov_b32_e32 v46, 0
	v_mov_b32_e32 v47, 0
	s_and_saveexec_b64 s[28:29], s[26:27]
	v_mad_i64_i32 v[56:57], vcc, v2, s70, v[4:5]
	global_load_dword v40, v[56:57], off
	v_or_b32_e32 v56, 1, v2
	v_mad_i64_i32 v[56:57], vcc, v56, s70, v[4:5]
	global_load_dword v41, v[56:57], off
	v_or_b32_e32 v56, 2, v2
	v_mad_i64_i32 v[56:57], vcc, v56, s70, v[4:5]
	global_load_dword v42, v[56:57], off
	v_or_b32_e32 v56, 3, v2
	v_mad_i64_i32 v[56:57], vcc, v56, s70, v[4:5]
	global_load_dword v43, v[56:57], off
	v_or_b32_e32 v56, 4, v2
	v_mad_i64_i32 v[56:57], vcc, v56, s70, v[4:5]
	global_load_dword v44, v[56:57], off
	v_or_b32_e32 v56, 5, v2
	v_mad_i64_i32 v[56:57], vcc, v56, s70, v[4:5]
	global_load_dword v45, v[56:57], off
	v_or_b32_e32 v56, 6, v2
	v_mad_i64_i32 v[56:57], vcc, v56, s70, v[4:5]
	global_load_dword v46, v[56:57], off
	v_or_b32_e32 v56, 7, v2
	v_mad_i64_i32 v[56:57], vcc, v56, s70, v[4:5]
	global_load_dword v47, v[56:57], off
	s_or_b64 exec, exec, s[28:29]
	s_andn2_b64 vcc, exec, s[22:23]
	s_cbranch_vccnz .Lcvt_nog_1
	v_ashrrev_i32_e32 v3, 31, v2
	v_lshl_add_u64 v[14:15], v[2:3], 2, s[18:19]
	global_load_dword v48, v[14:15], off
	global_load_dword v49, v[14:15], off offset:4
	global_load_dword v50, v[14:15], off offset:8
	global_load_dword v51, v[14:15], off offset:12
	global_load_dword v52, v[14:15], off offset:16
	global_load_dword v53, v[14:15], off offset:20
	global_load_dword v54, v[14:15], off offset:24
	global_load_dword v55, v[14:15], off offset:28
	s_waitcnt vmcnt(0)
	v_mul_f32_e32 v40, v40, v48
	v_mul_f32_e32 v41, v41, v49
	v_mul_f32_e32 v42, v42, v50
	v_mul_f32_e32 v43, v43, v51
	v_mul_f32_e32 v44, v44, v52
	v_mul_f32_e32 v45, v45, v53
	v_mul_f32_e32 v46, v46, v54
	v_mul_f32_e32 v47, v47, v55

; template <class F> DI void cvt_wT(const float* W, int K, int Ns, bf16_t* Wt, int Nd, F smap, float* sl, const float* gsc = nullptr) {
;     ...
;         const int j = tid & 63, i = tid >> 6;
;         __syncthreads();
; #pragma unroll
;         for (int r = 0; r < 8; ++r) { const int k = k0 + i * 8 + r; float v = 0.f; if (s0 >= 0 && s0 + j < Ns) v = W[(size_t)k * Ns + s0 + j]; if (gsc) v *= gsc[k]; sl[(i * 8 + r) * 65 + j] = v; }
;         __syncthreads();
.LBB0_640:
	s_mul_hi_i32 s6, s26, 0x2e8ba2e9
	s_lshr_b32 s7, s6, 31
	s_ashr_i32 s6, s6, 4
	s_add_i32 s6, s6, s7
	s_mul_i32 s7, s6, 0xffffea00
	s_lshl_b32 s14, s6, 6
	s_mulk_i32 s6, 0xf500
	s_add_i32 s15, s28, s7
	s_bfe_i32 s7, s26, 0x10001
	s_add_i32 s6, s30, s6
	s_and_b32 s7, s7, 0xb00
	s_and_b32 s6, s6, 0xffffff80
	s_add_i32 s7, s7, s6
	s_and_b32 s6, s15, 64
	s_or_b32 s98, s7, s6
	s_cmp_gt_i32 s7, -1
	v_or_b32_e32 v3, s98, v6
	s_cselect_b64 s[6:7], -1, 0
	v_cmp_gt_i32_e32 vcc, s91, v3
	v_add_u32_e32 v2, s14, v8
	s_and_b64 s[16:17], s[6:7], vcc
	v_lshl_add_u64 v[4:5], s[98:99], 2, v[0:1]
	v_mov_b32_e32 v12, 0
	s_barrier
	v_mov_b32_e32 v40, 0
	v_mov_b32_e32 v41, 0
	v_mov_b32_e32 v42, 0
	v_mov_b32_e32 v43, 0
	v_mov_b32_e32 v44, 0
	v_mov_b32_e32 v45, 0
	v_mov_b32_e32 v46, 0
	v_mov_b32_e32 v47, 0
	s_and_saveexec_b64 s[18:19], s[16:17]
	v_mad_i64_i32 v[56:57], vcc, v2, s82, v[4:5]
	global_load_dword v40, v[56:57], off
	v_or_b32_e32 v56, 1, v2
	v_mad_i64_i32 v[56:57], vcc, v56, s82, v[4:5]
	global_load_dword v41, v[56:57], off
	v_or_b32_e32 v56, 2, v2
	v_mad_i64_i32 v[56:57], vcc, v56, s82, v[4:5]
	global_load_dword v42, v[56:57], off
	v_or_b32_e32 v56, 3, v2
	v_mad_i64_i32 v[56:57], vcc, v56, s82, v[4:5]
	global_load_dword v43, v[56:57], off
	v_or_b32_e32 v56, 4, v2
	v_mad_i64_i32 v[56:57], vcc, v56, s82, v[4:5]
	global_load_dword v44, v[56:57], off
	v_or_b32_e32 v56, 5, v2
	v_mad_i64_i32 v[56:57], vcc, v56, s82, v[4:5]
	global_load_dword v45, v[56:57], off
	v_or_b32_e32 v56, 6, v2
	v_mad_i64_i32 v[56:57], vcc, v56, s82, v[4:5]
	global_load_dword v46, v[56:57], off
	v_or_b32_e32 v56, 7, v2
	v_mad_i64_i32 v[56:57], vcc, v56, s82, v[4:5]
	global_load_dword v47, v[56:57], off
	s_or_b64 exec, exec, s[18:19]
	s_andn2_b64 vcc, exec, s[0:1]
	s_cbranch_vccnz .Lcvt_nog_2
	v_ashrrev_i32_e32 v3, 31, v2
	v_lshl_add_u64 v[14:15], v[2:3], 2, s[12:13]
	global_load_dword v48, v[14:15], off
	global_load_dword v49, v[14:15], off offset:4
	global_load_dword v50, v[14:15], off offset:8
	global_load_dword v51, v[14:15], off offset:12
	global_load_dword v52, v[14:15], off offset:16
	global_load_dword v53, v[14:15], off offset:20
	global_load_dword v54, v[14:15], off offset:24
	global_load_dword v55, v[14:15], off offset:28
	s_waitcnt vmcnt(0)
	v_mul_f32_e32 v40, v40, v48
	v_mul_f32_e32 v41, v41, v49
	v_mul_f32_e32 v42, v42, v50
	v_mul_f32_e32 v43, v43, v51
	v_mul_f32_e32 v44, v44, v52
	v_mul_f32_e32 v45, v45, v53
	v_mul_f32_e32 v46, v46, v54
	v_mul_f32_e32 v47, v47, v55
